# v1 + GLA prep phase rewritten by hand: lanes own 2 channels (dword accesses), waves own 8 tokens, gate vectors via scalar loads as SGPR FMA operands, one barrier per item
# speedup vs baseline: 1.0402x; 1.0360x over previous
.LBB0_777:
	s_cmp_lt_i32 s90, 8
	s_cselect_b64 s[2:3], -1, 0
	s_add_u32 s36, s88, 0x115d000
	s_addc_u32 s37, s89, 0
	s_and_b64 s[18:19], s[2:3], s[0:1]
	s_andn2_b64 vcc, exec, s[18:19]
	s_cbranch_vccnz .LBB0_852
	s_cmpk_gt_i32 s58, 0x47f
	s_cbranch_scc1 .LBB0_851
	v_writelane_b32 v252, s18, 0
	v_writelane_b32 v252, s19, 1
	v_writelane_b32 v252, s24, 2
	v_writelane_b32 v252, s25, 3
	v_writelane_b32 v252, s26, 4
	v_writelane_b32 v252, s27, 5
	s_waitcnt vmcnt(0)
	v_readfirstlane_b32 s32, v0
	v_and_b32_e32 v2, 63, v0
	s_mov_b32 s33, 0xbfb8aa3b
	s_mov_b32 s35, 0x3f317217
	s_lshr_b32 s32, s32, 6
	v_lshlrev_b32_e32 v3, 3, v2
	v_lshlrev_b32_e32 v2, 2, v2
	s_mov_b32 s34, s58
	s_mov_b32 s98, 0
.Lp7_item:
	s_mul_hi_u32 s99, s34, 0x1c71c72
	s_mul_i32 s92, s99, 144
	s_sub_i32 s92, s34, s92
	s_mul_hi_u32 s101, s92, 0x71c71c8
	s_mul_i32 s93, s101, 36
	s_sub_i32 s100, s92, s93
	s_lshl_b32 s92, s99, 8
	s_lshl_b32 s93, s100, 6
	s_add_i32 s92, s92, s93
	s_addk_i32 s92, 0x4000
	s_lshl_b32 s94, s99, 11
	s_add_i32 s94, s94, s93
	s_addk_i32 s94, 0xff00
	s_cmp_lt_u32 s100, 4
	s_cselect_b32 s54, s92, s94
	s_lshl_b32 s92, s32, 3
	s_add_i32 s54, s54, s92
	s_lshl_b32 s95, s101, 9
	v_readlane_b32 s52, v251, 18
	v_readlane_b32 s53, v251, 19
	s_nop 3
	s_add_u32 s52, s52, s95
	s_addc_u32 s53, s53, 0
	s_nop 3
	global_load_dwordx2 v[10:11], v3, s[52:53]
	global_load_dwordx2 v[12:13], v3, s[52:53] offset:2048
	s_add_u32 s52, s52, 0x1000
	s_addc_u32 s53, s53, 0
	global_load_dwordx2 v[14:15], v3, s[52:53]
	global_load_dwordx2 v[16:17], v3, s[52:53] offset:2048
	s_add_u32 s52, s52, 0x1000
	s_addc_u32 s53, s53, 0
	global_load_dwordx2 v[18:19], v3, s[52:53]
	global_load_dwordx2 v[20:21], v3, s[52:53] offset:2048
	s_add_u32 s52, s52, 0x1000
	s_addc_u32 s53, s53, 0
	global_load_dwordx2 v[22:23], v3, s[52:53]
	global_load_dwordx2 v[24:25], v3, s[52:53] offset:2048
	s_add_u32 s52, s52, 0x1000
	s_addc_u32 s53, s53, 0
	global_load_dwordx2 v[26:27], v3, s[52:53]
	global_load_dwordx2 v[28:29], v3, s[52:53] offset:2048
	s_add_u32 s52, s52, 0x1000
	s_addc_u32 s53, s53, 0
	global_load_dwordx2 v[30:31], v3, s[52:53]
	global_load_dwordx2 v[32:33], v3, s[52:53] offset:2048
	s_add_u32 s52, s52, 0x1000
	s_addc_u32 s53, s53, 0
	global_load_dwordx2 v[34:35], v3, s[52:53]
	global_load_dwordx2 v[36:37], v3, s[52:53] offset:2048
	s_add_u32 s52, s52, 0x1000
	s_addc_u32 s53, s53, 0
	global_load_dwordx2 v[38:39], v3, s[52:53]
	global_load_dwordx2 v[40:41], v3, s[52:53] offset:2048
	v_readlane_b32 s52, v251, 24
	v_readlane_b32 s53, v251, 25
	s_nop 3
	s_add_u32 s52, s52, s95
	s_addc_u32 s53, s53, 0
	s_nop 3
	global_load_dwordx2 v[42:43], v3, s[52:53]
	global_load_dwordx2 v[44:45], v3, s[52:53] offset:2048
	s_add_u32 s52, s52, 0x1000
	s_addc_u32 s53, s53, 0
	global_load_dwordx2 v[46:47], v3, s[52:53]
	global_load_dwordx2 v[48:49], v3, s[52:53] offset:2048
	s_add_u32 s52, s52, 0x1000
	s_addc_u32 s53, s53, 0
	global_load_dwordx2 v[50:51], v3, s[52:53]
	global_load_dwordx2 v[52:53], v3, s[52:53] offset:2048
	s_add_u32 s52, s52, 0x1000
	s_addc_u32 s53, s53, 0
	global_load_dwordx2 v[54:55], v3, s[52:53]
	global_load_dwordx2 v[56:57], v3, s[52:53] offset:2048
	s_add_u32 s52, s52, 0x1000
	s_addc_u32 s53, s53, 0
	global_load_dwordx2 v[58:59], v3, s[52:53]
	global_load_dwordx2 v[60:61], v3, s[52:53] offset:2048
	s_add_u32 s52, s52, 0x1000
	s_addc_u32 s53, s53, 0
	global_load_dwordx2 v[62:63], v3, s[52:53]
	global_load_dwordx2 v[64:65], v3, s[52:53] offset:2048
	s_add_u32 s52, s52, 0x1000
	s_addc_u32 s53, s53, 0
	global_load_dwordx2 v[66:67], v3, s[52:53]
	global_load_dwordx2 v[68:69], v3, s[52:53] offset:2048
	s_add_u32 s52, s52, 0x1000
	s_addc_u32 s53, s53, 0
	global_load_dwordx2 v[70:71], v3, s[52:53]
	global_load_dwordx2 v[72:73], v3, s[52:53] offset:2048
	v_readlane_b32 s52, v251, 20
	v_readlane_b32 s53, v251, 21
	s_nop 3
	s_add_u32 s52, s52, s95
	s_addc_u32 s53, s53, 0
	s_nop 3
	global_load_dwordx2 v[74:75], v3, s[52:53]
	v_readlane_b32 s52, v251, 26
	v_readlane_b32 s53, v251, 27
	s_nop 3
	s_add_u32 s52, s52, s95
	s_addc_u32 s53, s53, 0
	s_nop 3
	global_load_dwordx2 v[76:77], v3, s[52:53]
	s_lshl_b32 s95, s101, 8
	s_mul_i32 s92, s54, 0x1800
	s_add_u32 s92, s92, s95
	s_add_u32 s80, s96, s92
	s_addc_u32 s81, s97, 0
	s_lshl_b32 s92, s54, 10
	s_add_u32 s92, s92, s95
	s_add_u32 s84, s88, 0xa27d000
	s_addc_u32 s85, s89, 0
	s_add_u32 s84, s84, s92
	s_addc_u32 s85, s85, 0
	s_add_u32 s82, s84, 0x1000000
	s_addc_u32 s83, s85, 0
	s_lshl_b32 s92, s54, 7
	s_add_u32 s86, s88, 0xf1d000
	s_addc_u32 s87, s89, 0
	s_add_u32 s86, s86, s92
	s_addc_u32 s87, s87, 0
	s_load_dwordx16 s[0:15], s[86:87], 0x0
	s_load_dwordx16 s[64:79], s[86:87], 0x40
	s_mov_b64 s[52:53], s[80:81]
	global_load_dword v80, v2, s[52:53] offset:1024
	s_add_u32 s52, s52, 0x1800
	s_addc_u32 s53, s53, 0
	global_load_dword v81, v2, s[52:53] offset:1024
	s_add_u32 s52, s52, 0x1800
	s_addc_u32 s53, s53, 0
	global_load_dword v82, v2, s[52:53] offset:1024
	s_add_u32 s52, s52, 0x1800
	s_addc_u32 s53, s53, 0
	global_load_dword v83, v2, s[52:53] offset:1024
	s_add_u32 s52, s52, 0x1800
	s_addc_u32 s53, s53, 0
	global_load_dword v84, v2, s[52:53] offset:1024
	s_add_u32 s52, s52, 0x1800
	s_addc_u32 s53, s53, 0
	global_load_dword v85, v2, s[52:53] offset:1024
	s_add_u32 s52, s52, 0x1800
	s_addc_u32 s53, s53, 0
	global_load_dword v86, v2, s[52:53] offset:1024
	s_add_u32 s52, s52, 0x1800
	s_addc_u32 s53, s53, 0
	global_load_dword v87, v2, s[52:53] offset:1024
	s_cmp_lt_u32 s100, 4
	s_cbranch_scc1 .Lp7_noq_load
	s_mov_b64 s[52:53], s[80:81]
	global_load_dword v88, v2, s[52:53]
	s_add_u32 s52, s52, 0x1800
	s_addc_u32 s53, s53, 0
	global_load_dword v89, v2, s[52:53]
	s_add_u32 s52, s52, 0x1800
	s_addc_u32 s53, s53, 0
	global_load_dword v90, v2, s[52:53]
	s_add_u32 s52, s52, 0x1800
	s_addc_u32 s53, s53, 0
	global_load_dword v91, v2, s[52:53]
	s_add_u32 s52, s52, 0x1800
	s_addc_u32 s53, s53, 0
	global_load_dword v92, v2, s[52:53]
	s_add_u32 s52, s52, 0x1800
	s_addc_u32 s53, s53, 0
	global_load_dword v93, v2, s[52:53]
	s_add_u32 s52, s52, 0x1800
	s_addc_u32 s53, s53, 0
	global_load_dword v94, v2, s[52:53]
	s_add_u32 s52, s52, 0x1800
	s_addc_u32 s53, s53, 0
	global_load_dword v95, v2, s[52:53]
.Lp7_noq_load:
	s_waitcnt vmcnt(0)
	s_waitcnt lgkmcnt(0)
	s_add_u32 s86, s86, 0x80
	s_addc_u32 s87, s87, 0
	s_load_dwordx16 s[16:31], s[86:87], 0x0
	s_load_dwordx16 s[36:51], s[86:87], 0x40
	v_fma_f32 v128, s0, v10, v74
	v_fma_f32 v129, s0, v11, v75
	v_fma_f32 v130, s64, v42, v76
	v_fma_f32 v131, s64, v43, v77
	v_fmac_f32_e32 v128, s1, v12
	v_fmac_f32_e32 v129, s1, v13
	v_fmac_f32_e32 v130, s65, v44
	v_fmac_f32_e32 v131, s65, v45
	v_fmac_f32_e32 v128, s2, v14
	v_fmac_f32_e32 v129, s2, v15
	v_fmac_f32_e32 v130, s66, v46
	v_fmac_f32_e32 v131, s66, v47
	v_fmac_f32_e32 v128, s3, v16
	v_fmac_f32_e32 v129, s3, v17
	v_fmac_f32_e32 v130, s67, v48
	v_fmac_f32_e32 v131, s67, v49
	v_fmac_f32_e32 v128, s4, v18
	v_fmac_f32_e32 v129, s4, v19
	v_fmac_f32_e32 v130, s68, v50
	v_fmac_f32_e32 v131, s68, v51
	v_fmac_f32_e32 v128, s5, v20
	v_fmac_f32_e32 v129, s5, v21
	v_fmac_f32_e32 v130, s69, v52
	v_fmac_f32_e32 v131, s69, v53
	v_fmac_f32_e32 v128, s6, v22
	v_fmac_f32_e32 v129, s6, v23
	v_fmac_f32_e32 v130, s70, v54
	v_fmac_f32_e32 v131, s70, v55
	v_fmac_f32_e32 v128, s7, v24
	v_fmac_f32_e32 v129, s7, v25
	v_fmac_f32_e32 v130, s71, v56
	v_fmac_f32_e32 v131, s71, v57
	v_fmac_f32_e32 v128, s8, v26
	v_fmac_f32_e32 v129, s8, v27
	v_fmac_f32_e32 v130, s72, v58
	v_fmac_f32_e32 v131, s72, v59
	v_fmac_f32_e32 v128, s9, v28
	v_fmac_f32_e32 v129, s9, v29
	v_fmac_f32_e32 v130, s73, v60
	v_fmac_f32_e32 v131, s73, v61
	v_fmac_f32_e32 v128, s10, v30
	v_fmac_f32_e32 v129, s10, v31
	v_fmac_f32_e32 v130, s74, v62
	v_fmac_f32_e32 v131, s74, v63
	v_fmac_f32_e32 v128, s11, v32
	v_fmac_f32_e32 v129, s11, v33
	v_fmac_f32_e32 v130, s75, v64
	v_fmac_f32_e32 v131, s75, v65
	v_fmac_f32_e32 v128, s12, v34
	v_fmac_f32_e32 v129, s12, v35
	v_fmac_f32_e32 v130, s76, v66
	v_fmac_f32_e32 v131, s76, v67
	v_fmac_f32_e32 v128, s13, v36
	v_fmac_f32_e32 v129, s13, v37
	v_fmac_f32_e32 v130, s77, v68
	v_fmac_f32_e32 v131, s77, v69
	v_fmac_f32_e32 v128, s14, v38
	v_fmac_f32_e32 v129, s14, v39
	v_fmac_f32_e32 v130, s78, v70
	v_fmac_f32_e32 v131, s78, v71
	v_fmac_f32_e32 v128, s15, v40
	v_fmac_f32_e32 v129, s15, v41
	v_fmac_f32_e32 v130, s79, v72
	v_fmac_f32_e32 v131, s79, v73
	v_mul_f32_e64 v132, |v128|, s33
	v_mul_f32_e64 v133, |v129|, s33
	v_mul_f32_e64 v134, |v130|, s33
	v_mul_f32_e64 v135, |v131|, s33
	v_exp_f32_e32 v132, v132
	v_exp_f32_e32 v133, v133
	v_exp_f32_e32 v134, v134
	v_exp_f32_e32 v135, v135
	v_add_f32_e32 v132, 1.0, v132
	v_add_f32_e32 v133, 1.0, v133
	v_add_f32_e32 v134, 1.0, v134
	v_add_f32_e32 v135, 1.0, v135
	v_log_f32_e32 v136, v132
	v_log_f32_e32 v137, v133
	v_log_f32_e32 v138, v134
	v_log_f32_e32 v139, v135
	v_mul_f32_e32 v140, 0x3f317217, v136
	v_mul_f32_e32 v141, 0x3f317217, v137
	v_mul_f32_e32 v142, 0x3f317217, v138
	v_mul_f32_e32 v143, 0x3f317217, v139
	v_fma_f32 v144, v136, s35, -v140
	v_fma_f32 v145, v137, s35, -v141
	v_fma_f32 v146, v138, s35, -v142
	v_fma_f32 v147, v139, s35, -v143
	v_fmac_f32_e32 v144, 0x3377d1cf, v136
	v_fmac_f32_e32 v145, 0x3377d1cf, v137
	v_fmac_f32_e32 v146, 0x3377d1cf, v138
	v_fmac_f32_e32 v147, 0x3377d1cf, v139
	v_fmac_f32_e32 v144, 0x3f317217, v136
	v_fmac_f32_e32 v145, 0x3f317217, v137
	v_fmac_f32_e32 v146, 0x3f317217, v138
	v_fmac_f32_e32 v147, 0x3f317217, v139
	v_min_f32_e32 v128, 0, v128
	v_min_f32_e32 v129, 0, v129
	v_min_f32_e32 v130, 0, v130
	v_min_f32_e32 v131, 0, v131
	v_sub_f32_e32 v128, v128, v144
	v_sub_f32_e32 v129, v129, v145
	v_sub_f32_e32 v130, v130, v146
	v_sub_f32_e32 v131, v131, v147
	v_mul_f32_e32 v96, 0x3d800000, v128
	v_mul_f32_e32 v97, 0x3d800000, v129
	v_mul_f32_e32 v112, 0x3d800000, v130
	v_mul_f32_e32 v113, 0x3d800000, v131
	s_waitcnt lgkmcnt(0)
	s_add_u32 s86, s86, 0x80
	s_addc_u32 s87, s87, 0
	s_load_dwordx16 s[0:15], s[86:87], 0x0
	s_load_dwordx16 s[64:79], s[86:87], 0x40
	v_fma_f32 v128, s16, v10, v74
	v_fma_f32 v129, s16, v11, v75
	v_fma_f32 v130, s36, v42, v76
	v_fma_f32 v131, s36, v43, v77
	v_fmac_f32_e32 v128, s17, v12
	v_fmac_f32_e32 v129, s17, v13
	v_fmac_f32_e32 v130, s37, v44
	v_fmac_f32_e32 v131, s37, v45
	v_fmac_f32_e32 v128, s18, v14
	v_fmac_f32_e32 v129, s18, v15
	v_fmac_f32_e32 v130, s38, v46
	v_fmac_f32_e32 v131, s38, v47
	v_fmac_f32_e32 v128, s19, v16
	v_fmac_f32_e32 v129, s19, v17
	v_fmac_f32_e32 v130, s39, v48
	v_fmac_f32_e32 v131, s39, v49
	v_fmac_f32_e32 v128, s20, v18
	v_fmac_f32_e32 v129, s20, v19
	v_fmac_f32_e32 v130, s40, v50
	v_fmac_f32_e32 v131, s40, v51
	v_fmac_f32_e32 v128, s21, v20
	v_fmac_f32_e32 v129, s21, v21
	v_fmac_f32_e32 v130, s41, v52
	v_fmac_f32_e32 v131, s41, v53
	v_fmac_f32_e32 v128, s22, v22
	v_fmac_f32_e32 v129, s22, v23
	v_fmac_f32_e32 v130, s42, v54
	v_fmac_f32_e32 v131, s42, v55
	v_fmac_f32_e32 v128, s23, v24
	v_fmac_f32_e32 v129, s23, v25
	v_fmac_f32_e32 v130, s43, v56
	v_fmac_f32_e32 v131, s43, v57
	v_fmac_f32_e32 v128, s24, v26
	v_fmac_f32_e32 v129, s24, v27
	v_fmac_f32_e32 v130, s44, v58
	v_fmac_f32_e32 v131, s44, v59
	v_fmac_f32_e32 v128, s25, v28
	v_fmac_f32_e32 v129, s25, v29
	v_fmac_f32_e32 v130, s45, v60
	v_fmac_f32_e32 v131, s45, v61
	v_fmac_f32_e32 v128, s26, v30
	v_fmac_f32_e32 v129, s26, v31
	v_fmac_f32_e32 v130, s46, v62
	v_fmac_f32_e32 v131, s46, v63
	v_fmac_f32_e32 v128, s27, v32
	v_fmac_f32_e32 v129, s27, v33
	v_fmac_f32_e32 v130, s47, v64
	v_fmac_f32_e32 v131, s47, v65
	v_fmac_f32_e32 v128, s28, v34
	v_fmac_f32_e32 v129, s28, v35
	v_fmac_f32_e32 v130, s48, v66
	v_fmac_f32_e32 v131, s48, v67
	v_fmac_f32_e32 v128, s29, v36
	v_fmac_f32_e32 v129, s29, v37
	v_fmac_f32_e32 v130, s49, v68
	v_fmac_f32_e32 v131, s49, v69
	v_fmac_f32_e32 v128, s30, v38
	v_fmac_f32_e32 v129, s30, v39
	v_fmac_f32_e32 v130, s50, v70
	v_fmac_f32_e32 v131, s50, v71
	v_fmac_f32_e32 v128, s31, v40
	v_fmac_f32_e32 v129, s31, v41
	v_fmac_f32_e32 v130, s51, v72
	v_fmac_f32_e32 v131, s51, v73
	v_mul_f32_e64 v132, |v128|, s33
	v_mul_f32_e64 v133, |v129|, s33
	v_mul_f32_e64 v134, |v130|, s33
	v_mul_f32_e64 v135, |v131|, s33
	v_exp_f32_e32 v132, v132
	v_exp_f32_e32 v133, v133
	v_exp_f32_e32 v134, v134
	v_exp_f32_e32 v135, v135
	v_add_f32_e32 v132, 1.0, v132
	v_add_f32_e32 v133, 1.0, v133
	v_add_f32_e32 v134, 1.0, v134
	v_add_f32_e32 v135, 1.0, v135
	v_log_f32_e32 v136, v132
	v_log_f32_e32 v137, v133
	v_log_f32_e32 v138, v134
	v_log_f32_e32 v139, v135
	v_mul_f32_e32 v140, 0x3f317217, v136
	v_mul_f32_e32 v141, 0x3f317217, v137
	v_mul_f32_e32 v142, 0x3f317217, v138
	v_mul_f32_e32 v143, 0x3f317217, v139
	v_fma_f32 v144, v136, s35, -v140
	v_fma_f32 v145, v137, s35, -v141
	v_fma_f32 v146, v138, s35, -v142
	v_fma_f32 v147, v139, s35, -v143
	v_fmac_f32_e32 v144, 0x3377d1cf, v136
	v_fmac_f32_e32 v145, 0x3377d1cf, v137
	v_fmac_f32_e32 v146, 0x3377d1cf, v138
	v_fmac_f32_e32 v147, 0x3377d1cf, v139
	v_fmac_f32_e32 v144, 0x3f317217, v136
	v_fmac_f32_e32 v145, 0x3f317217, v137
	v_fmac_f32_e32 v146, 0x3f317217, v138
	v_fmac_f32_e32 v147, 0x3f317217, v139
	v_min_f32_e32 v128, 0, v128
	v_min_f32_e32 v129, 0, v129
	v_min_f32_e32 v130, 0, v130
	v_min_f32_e32 v131, 0, v131
	v_sub_f32_e32 v128, v128, v144
	v_sub_f32_e32 v129, v129, v145
	v_sub_f32_e32 v130, v130, v146
	v_sub_f32_e32 v131, v131, v147
	v_mul_f32_e32 v98, 0x3d800000, v128
	v_mul_f32_e32 v99, 0x3d800000, v129
	v_mul_f32_e32 v114, 0x3d800000, v130
	v_mul_f32_e32 v115, 0x3d800000, v131
	s_waitcnt lgkmcnt(0)
	s_add_u32 s86, s86, 0x80
	s_addc_u32 s87, s87, 0
	s_load_dwordx16 s[16:31], s[86:87], 0x0
	s_load_dwordx16 s[36:51], s[86:87], 0x40
	v_fma_f32 v128, s0, v10, v74
	v_fma_f32 v129, s0, v11, v75
	v_fma_f32 v130, s64, v42, v76
	v_fma_f32 v131, s64, v43, v77
	v_fmac_f32_e32 v128, s1, v12
	v_fmac_f32_e32 v129, s1, v13
	v_fmac_f32_e32 v130, s65, v44
	v_fmac_f32_e32 v131, s65, v45
	v_fmac_f32_e32 v128, s2, v14
	v_fmac_f32_e32 v129, s2, v15
	v_fmac_f32_e32 v130, s66, v46
	v_fmac_f32_e32 v131, s66, v47
	v_fmac_f32_e32 v128, s3, v16
	v_fmac_f32_e32 v129, s3, v17
	v_fmac_f32_e32 v130, s67, v48
	v_fmac_f32_e32 v131, s67, v49
	v_fmac_f32_e32 v128, s4, v18
	v_fmac_f32_e32 v129, s4, v19
	v_fmac_f32_e32 v130, s68, v50
	v_fmac_f32_e32 v131, s68, v51
	v_fmac_f32_e32 v128, s5, v20
	v_fmac_f32_e32 v129, s5, v21
	v_fmac_f32_e32 v130, s69, v52
	v_fmac_f32_e32 v131, s69, v53
	v_fmac_f32_e32 v128, s6, v22
	v_fmac_f32_e32 v129, s6, v23
	v_fmac_f32_e32 v130, s70, v54
	v_fmac_f32_e32 v131, s70, v55
	v_fmac_f32_e32 v128, s7, v24
	v_fmac_f32_e32 v129, s7, v25
	v_fmac_f32_e32 v130, s71, v56
	v_fmac_f32_e32 v131, s71, v57
	v_fmac_f32_e32 v128, s8, v26
	v_fmac_f32_e32 v129, s8, v27
	v_fmac_f32_e32 v130, s72, v58
	v_fmac_f32_e32 v131, s72, v59
	v_fmac_f32_e32 v128, s9, v28
	v_fmac_f32_e32 v129, s9, v29
	v_fmac_f32_e32 v130, s73, v60
	v_fmac_f32_e32 v131, s73, v61
	v_fmac_f32_e32 v128, s10, v30
	v_fmac_f32_e32 v129, s10, v31
	v_fmac_f32_e32 v130, s74, v62
	v_fmac_f32_e32 v131, s74, v63
	v_fmac_f32_e32 v128, s11, v32
	v_fmac_f32_e32 v129, s11, v33
	v_fmac_f32_e32 v130, s75, v64
	v_fmac_f32_e32 v131, s75, v65
	v_fmac_f32_e32 v128, s12, v34
	v_fmac_f32_e32 v129, s12, v35
	v_fmac_f32_e32 v130, s76, v66
	v_fmac_f32_e32 v131, s76, v67
	v_fmac_f32_e32 v128, s13, v36
	v_fmac_f32_e32 v129, s13, v37
	v_fmac_f32_e32 v130, s77, v68
	v_fmac_f32_e32 v131, s77, v69
	v_fmac_f32_e32 v128, s14, v38
	v_fmac_f32_e32 v129, s14, v39
	v_fmac_f32_e32 v130, s78, v70
	v_fmac_f32_e32 v131, s78, v71
	v_fmac_f32_e32 v128, s15, v40
	v_fmac_f32_e32 v129, s15, v41
	v_fmac_f32_e32 v130, s79, v72
	v_fmac_f32_e32 v131, s79, v73
	v_mul_f32_e64 v132, |v128|, s33
	v_mul_f32_e64 v133, |v129|, s33
	v_mul_f32_e64 v134, |v130|, s33
	v_mul_f32_e64 v135, |v131|, s33
	v_exp_f32_e32 v132, v132
	v_exp_f32_e32 v133, v133
	v_exp_f32_e32 v134, v134
	v_exp_f32_e32 v135, v135
	v_add_f32_e32 v132, 1.0, v132
	v_add_f32_e32 v133, 1.0, v133
	v_add_f32_e32 v134, 1.0, v134
	v_add_f32_e32 v135, 1.0, v135
	v_log_f32_e32 v136, v132
	v_log_f32_e32 v137, v133
	v_log_f32_e32 v138, v134
	v_log_f32_e32 v139, v135
	v_mul_f32_e32 v140, 0x3f317217, v136
	v_mul_f32_e32 v141, 0x3f317217, v137
	v_mul_f32_e32 v142, 0x3f317217, v138
	v_mul_f32_e32 v143, 0x3f317217, v139
	v_fma_f32 v144, v136, s35, -v140
	v_fma_f32 v145, v137, s35, -v141
	v_fma_f32 v146, v138, s35, -v142
	v_fma_f32 v147, v139, s35, -v143
	v_fmac_f32_e32 v144, 0x3377d1cf, v136
	v_fmac_f32_e32 v145, 0x3377d1cf, v137
	v_fmac_f32_e32 v146, 0x3377d1cf, v138
	v_fmac_f32_e32 v147, 0x3377d1cf, v139
	v_fmac_f32_e32 v144, 0x3f317217, v136
	v_fmac_f32_e32 v145, 0x3f317217, v137
	v_fmac_f32_e32 v146, 0x3f317217, v138
	v_fmac_f32_e32 v147, 0x3f317217, v139
	v_min_f32_e32 v128, 0, v128
	v_min_f32_e32 v129, 0, v129
	v_min_f32_e32 v130, 0, v130
	v_min_f32_e32 v131, 0, v131
	v_sub_f32_e32 v128, v128, v144
	v_sub_f32_e32 v129, v129, v145
	v_sub_f32_e32 v130, v130, v146
	v_sub_f32_e32 v131, v131, v147
	v_mul_f32_e32 v100, 0x3d800000, v128
	v_mul_f32_e32 v101, 0x3d800000, v129
	v_mul_f32_e32 v116, 0x3d800000, v130
	v_mul_f32_e32 v117, 0x3d800000, v131
	s_waitcnt lgkmcnt(0)
	s_add_u32 s86, s86, 0x80
	s_addc_u32 s87, s87, 0
	s_load_dwordx16 s[0:15], s[86:87], 0x0
	s_load_dwordx16 s[64:79], s[86:87], 0x40
	v_fma_f32 v128, s16, v10, v74
	v_fma_f32 v129, s16, v11, v75
	v_fma_f32 v130, s36, v42, v76
	v_fma_f32 v131, s36, v43, v77
	v_fmac_f32_e32 v128, s17, v12
	v_fmac_f32_e32 v129, s17, v13
	v_fmac_f32_e32 v130, s37, v44
	v_fmac_f32_e32 v131, s37, v45
	v_fmac_f32_e32 v128, s18, v14
	v_fmac_f32_e32 v129, s18, v15
	v_fmac_f32_e32 v130, s38, v46
	v_fmac_f32_e32 v131, s38, v47
	v_fmac_f32_e32 v128, s19, v16
	v_fmac_f32_e32 v129, s19, v17
	v_fmac_f32_e32 v130, s39, v48
	v_fmac_f32_e32 v131, s39, v49
	v_fmac_f32_e32 v128, s20, v18
	v_fmac_f32_e32 v129, s20, v19
	v_fmac_f32_e32 v130, s40, v50
	v_fmac_f32_e32 v131, s40, v51
	v_fmac_f32_e32 v128, s21, v20
	v_fmac_f32_e32 v129, s21, v21
	v_fmac_f32_e32 v130, s41, v52
	v_fmac_f32_e32 v131, s41, v53
	v_fmac_f32_e32 v128, s22, v22
	v_fmac_f32_e32 v129, s22, v23
	v_fmac_f32_e32 v130, s42, v54
	v_fmac_f32_e32 v131, s42, v55
	v_fmac_f32_e32 v128, s23, v24
	v_fmac_f32_e32 v129, s23, v25
	v_fmac_f32_e32 v130, s43, v56
	v_fmac_f32_e32 v131, s43, v57
	v_fmac_f32_e32 v128, s24, v26
	v_fmac_f32_e32 v129, s24, v27
	v_fmac_f32_e32 v130, s44, v58
	v_fmac_f32_e32 v131, s44, v59
	v_fmac_f32_e32 v128, s25, v28
	v_fmac_f32_e32 v129, s25, v29
	v_fmac_f32_e32 v130, s45, v60
	v_fmac_f32_e32 v131, s45, v61
	v_fmac_f32_e32 v128, s26, v30
	v_fmac_f32_e32 v129, s26, v31
	v_fmac_f32_e32 v130, s46, v62
	v_fmac_f32_e32 v131, s46, v63
	v_fmac_f32_e32 v128, s27, v32
	v_fmac_f32_e32 v129, s27, v33
	v_fmac_f32_e32 v130, s47, v64
	v_fmac_f32_e32 v131, s47, v65
	v_fmac_f32_e32 v128, s28, v34
	v_fmac_f32_e32 v129, s28, v35
	v_fmac_f32_e32 v130, s48, v66
	v_fmac_f32_e32 v131, s48, v67
	v_fmac_f32_e32 v128, s29, v36
	v_fmac_f32_e32 v129, s29, v37
	v_fmac_f32_e32 v130, s49, v68
	v_fmac_f32_e32 v131, s49, v69
	v_fmac_f32_e32 v128, s30, v38
	v_fmac_f32_e32 v129, s30, v39
	v_fmac_f32_e32 v130, s50, v70
	v_fmac_f32_e32 v131, s50, v71
	v_fmac_f32_e32 v128, s31, v40
	v_fmac_f32_e32 v129, s31, v41
	v_fmac_f32_e32 v130, s51, v72
	v_fmac_f32_e32 v131, s51, v73
	v_mul_f32_e64 v132, |v128|, s33
	v_mul_f32_e64 v133, |v129|, s33
	v_mul_f32_e64 v134, |v130|, s33
	v_mul_f32_e64 v135, |v131|, s33
	v_exp_f32_e32 v132, v132
	v_exp_f32_e32 v133, v133
	v_exp_f32_e32 v134, v134
	v_exp_f32_e32 v135, v135
	v_add_f32_e32 v132, 1.0, v132
	v_add_f32_e32 v133, 1.0, v133
	v_add_f32_e32 v134, 1.0, v134
	v_add_f32_e32 v135, 1.0, v135
	v_log_f32_e32 v136, v132
	v_log_f32_e32 v137, v133
	v_log_f32_e32 v138, v134
	v_log_f32_e32 v139, v135
	v_mul_f32_e32 v140, 0x3f317217, v136
	v_mul_f32_e32 v141, 0x3f317217, v137
	v_mul_f32_e32 v142, 0x3f317217, v138
	v_mul_f32_e32 v143, 0x3f317217, v139
	v_fma_f32 v144, v136, s35, -v140
	v_fma_f32 v145, v137, s35, -v141
	v_fma_f32 v146, v138, s35, -v142
	v_fma_f32 v147, v139, s35, -v143
	v_fmac_f32_e32 v144, 0x3377d1cf, v136
	v_fmac_f32_e32 v145, 0x3377d1cf, v137
	v_fmac_f32_e32 v146, 0x3377d1cf, v138
	v_fmac_f32_e32 v147, 0x3377d1cf, v139
	v_fmac_f32_e32 v144, 0x3f317217, v136
	v_fmac_f32_e32 v145, 0x3f317217, v137
	v_fmac_f32_e32 v146, 0x3f317217, v138
	v_fmac_f32_e32 v147, 0x3f317217, v139
	v_min_f32_e32 v128, 0, v128
	v_min_f32_e32 v129, 0, v129
	v_min_f32_e32 v130, 0, v130
	v_min_f32_e32 v131, 0, v131
	v_sub_f32_e32 v128, v128, v144
	v_sub_f32_e32 v129, v129, v145
	v_sub_f32_e32 v130, v130, v146
	v_sub_f32_e32 v131, v131, v147
	v_mul_f32_e32 v102, 0x3d800000, v128
	v_mul_f32_e32 v103, 0x3d800000, v129
	v_mul_f32_e32 v118, 0x3d800000, v130
	v_mul_f32_e32 v119, 0x3d800000, v131
	s_waitcnt lgkmcnt(0)
	s_add_u32 s86, s86, 0x80
	s_addc_u32 s87, s87, 0
	s_load_dwordx16 s[16:31], s[86:87], 0x0
	s_load_dwordx16 s[36:51], s[86:87], 0x40
	v_fma_f32 v128, s0, v10, v74
	v_fma_f32 v129, s0, v11, v75
	v_fma_f32 v130, s64, v42, v76
	v_fma_f32 v131, s64, v43, v77
	v_fmac_f32_e32 v128, s1, v12
	v_fmac_f32_e32 v129, s1, v13
	v_fmac_f32_e32 v130, s65, v44
	v_fmac_f32_e32 v131, s65, v45
	v_fmac_f32_e32 v128, s2, v14
	v_fmac_f32_e32 v129, s2, v15
	v_fmac_f32_e32 v130, s66, v46
	v_fmac_f32_e32 v131, s66, v47
	v_fmac_f32_e32 v128, s3, v16
	v_fmac_f32_e32 v129, s3, v17
	v_fmac_f32_e32 v130, s67, v48
	v_fmac_f32_e32 v131, s67, v49
	v_fmac_f32_e32 v128, s4, v18
	v_fmac_f32_e32 v129, s4, v19
	v_fmac_f32_e32 v130, s68, v50
	v_fmac_f32_e32 v131, s68, v51
	v_fmac_f32_e32 v128, s5, v20
	v_fmac_f32_e32 v129, s5, v21
	v_fmac_f32_e32 v130, s69, v52
	v_fmac_f32_e32 v131, s69, v53
	v_fmac_f32_e32 v128, s6, v22
	v_fmac_f32_e32 v129, s6, v23
	v_fmac_f32_e32 v130, s70, v54
	v_fmac_f32_e32 v131, s70, v55
	v_fmac_f32_e32 v128, s7, v24
	v_fmac_f32_e32 v129, s7, v25
	v_fmac_f32_e32 v130, s71, v56
	v_fmac_f32_e32 v131, s71, v57
	v_fmac_f32_e32 v128, s8, v26
	v_fmac_f32_e32 v129, s8, v27
	v_fmac_f32_e32 v130, s72, v58
	v_fmac_f32_e32 v131, s72, v59
	v_fmac_f32_e32 v128, s9, v28
	v_fmac_f32_e32 v129, s9, v29
	v_fmac_f32_e32 v130, s73, v60
	v_fmac_f32_e32 v131, s73, v61
	v_fmac_f32_e32 v128, s10, v30
	v_fmac_f32_e32 v129, s10, v31
	v_fmac_f32_e32 v130, s74, v62
	v_fmac_f32_e32 v131, s74, v63
	v_fmac_f32_e32 v128, s11, v32
	v_fmac_f32_e32 v129, s11, v33
	v_fmac_f32_e32 v130, s75, v64
	v_fmac_f32_e32 v131, s75, v65
	v_fmac_f32_e32 v128, s12, v34
	v_fmac_f32_e32 v129, s12, v35
	v_fmac_f32_e32 v130, s76, v66
	v_fmac_f32_e32 v131, s76, v67
	v_fmac_f32_e32 v128, s13, v36
	v_fmac_f32_e32 v129, s13, v37
	v_fmac_f32_e32 v130, s77, v68
	v_fmac_f32_e32 v131, s77, v69
	v_fmac_f32_e32 v128, s14, v38
	v_fmac_f32_e32 v129, s14, v39
	v_fmac_f32_e32 v130, s78, v70
	v_fmac_f32_e32 v131, s78, v71
	v_fmac_f32_e32 v128, s15, v40
	v_fmac_f32_e32 v129, s15, v41
	v_fmac_f32_e32 v130, s79, v72
	v_fmac_f32_e32 v131, s79, v73
	v_mul_f32_e64 v132, |v128|, s33
	v_mul_f32_e64 v133, |v129|, s33
	v_mul_f32_e64 v134, |v130|, s33
	v_mul_f32_e64 v135, |v131|, s33
	v_exp_f32_e32 v132, v132
	v_exp_f32_e32 v133, v133
	v_exp_f32_e32 v134, v134
	v_exp_f32_e32 v135, v135
	v_add_f32_e32 v132, 1.0, v132
	v_add_f32_e32 v133, 1.0, v133
	v_add_f32_e32 v134, 1.0, v134
	v_add_f32_e32 v135, 1.0, v135
	v_log_f32_e32 v136, v132
	v_log_f32_e32 v137, v133
	v_log_f32_e32 v138, v134
	v_log_f32_e32 v139, v135
	v_mul_f32_e32 v140, 0x3f317217, v136
	v_mul_f32_e32 v141, 0x3f317217, v137
	v_mul_f32_e32 v142, 0x3f317217, v138
	v_mul_f32_e32 v143, 0x3f317217, v139
	v_fma_f32 v144, v136, s35, -v140
	v_fma_f32 v145, v137, s35, -v141
	v_fma_f32 v146, v138, s35, -v142
	v_fma_f32 v147, v139, s35, -v143
	v_fmac_f32_e32 v144, 0x3377d1cf, v136
	v_fmac_f32_e32 v145, 0x3377d1cf, v137
	v_fmac_f32_e32 v146, 0x3377d1cf, v138
	v_fmac_f32_e32 v147, 0x3377d1cf, v139
	v_fmac_f32_e32 v144, 0x3f317217, v136
	v_fmac_f32_e32 v145, 0x3f317217, v137
	v_fmac_f32_e32 v146, 0x3f317217, v138
	v_fmac_f32_e32 v147, 0x3f317217, v139
	v_min_f32_e32 v128, 0, v128
	v_min_f32_e32 v129, 0, v129
	v_min_f32_e32 v130, 0, v130
	v_min_f32_e32 v131, 0, v131
	v_sub_f32_e32 v128, v128, v144
	v_sub_f32_e32 v129, v129, v145
	v_sub_f32_e32 v130, v130, v146
	v_sub_f32_e32 v131, v131, v147
	v_mul_f32_e32 v104, 0x3d800000, v128
	v_mul_f32_e32 v105, 0x3d800000, v129
	v_mul_f32_e32 v120, 0x3d800000, v130
	v_mul_f32_e32 v121, 0x3d800000, v131
	s_waitcnt lgkmcnt(0)
	s_add_u32 s86, s86, 0x80
	s_addc_u32 s87, s87, 0
	s_load_dwordx16 s[0:15], s[86:87], 0x0
	s_load_dwordx16 s[64:79], s[86:87], 0x40
	v_fma_f32 v128, s16, v10, v74
	v_fma_f32 v129, s16, v11, v75
	v_fma_f32 v130, s36, v42, v76
	v_fma_f32 v131, s36, v43, v77
	v_fmac_f32_e32 v128, s17, v12
	v_fmac_f32_e32 v129, s17, v13
	v_fmac_f32_e32 v130, s37, v44
	v_fmac_f32_e32 v131, s37, v45
	v_fmac_f32_e32 v128, s18, v14
	v_fmac_f32_e32 v129, s18, v15
	v_fmac_f32_e32 v130, s38, v46
	v_fmac_f32_e32 v131, s38, v47
	v_fmac_f32_e32 v128, s19, v16
	v_fmac_f32_e32 v129, s19, v17
	v_fmac_f32_e32 v130, s39, v48
	v_fmac_f32_e32 v131, s39, v49
	v_fmac_f32_e32 v128, s20, v18
	v_fmac_f32_e32 v129, s20, v19
	v_fmac_f32_e32 v130, s40, v50
	v_fmac_f32_e32 v131, s40, v51
	v_fmac_f32_e32 v128, s21, v20
	v_fmac_f32_e32 v129, s21, v21
	v_fmac_f32_e32 v130, s41, v52
	v_fmac_f32_e32 v131, s41, v53
	v_fmac_f32_e32 v128, s22, v22
	v_fmac_f32_e32 v129, s22, v23
	v_fmac_f32_e32 v130, s42, v54
	v_fmac_f32_e32 v131, s42, v55
	v_fmac_f32_e32 v128, s23, v24
	v_fmac_f32_e32 v129, s23, v25
	v_fmac_f32_e32 v130, s43, v56
	v_fmac_f32_e32 v131, s43, v57
	v_fmac_f32_e32 v128, s24, v26
	v_fmac_f32_e32 v129, s24, v27
	v_fmac_f32_e32 v130, s44, v58
	v_fmac_f32_e32 v131, s44, v59
	v_fmac_f32_e32 v128, s25, v28
	v_fmac_f32_e32 v129, s25, v29
	v_fmac_f32_e32 v130, s45, v60
	v_fmac_f32_e32 v131, s45, v61
	v_fmac_f32_e32 v128, s26, v30
	v_fmac_f32_e32 v129, s26, v31
	v_fmac_f32_e32 v130, s46, v62
	v_fmac_f32_e32 v131, s46, v63
	v_fmac_f32_e32 v128, s27, v32
	v_fmac_f32_e32 v129, s27, v33
	v_fmac_f32_e32 v130, s47, v64
	v_fmac_f32_e32 v131, s47, v65
	v_fmac_f32_e32 v128, s28, v34
	v_fmac_f32_e32 v129, s28, v35
	v_fmac_f32_e32 v130, s48, v66
	v_fmac_f32_e32 v131, s48, v67
	v_fmac_f32_e32 v128, s29, v36
	v_fmac_f32_e32 v129, s29, v37
	v_fmac_f32_e32 v130, s49, v68
	v_fmac_f32_e32 v131, s49, v69
	v_fmac_f32_e32 v128, s30, v38
	v_fmac_f32_e32 v129, s30, v39
	v_fmac_f32_e32 v130, s50, v70
	v_fmac_f32_e32 v131, s50, v71
	v_fmac_f32_e32 v128, s31, v40
	v_fmac_f32_e32 v129, s31, v41
	v_fmac_f32_e32 v130, s51, v72
	v_fmac_f32_e32 v131, s51, v73
	v_mul_f32_e64 v132, |v128|, s33
	v_mul_f32_e64 v133, |v129|, s33
	v_mul_f32_e64 v134, |v130|, s33
	v_mul_f32_e64 v135, |v131|, s33
	v_exp_f32_e32 v132, v132
	v_exp_f32_e32 v133, v133
	v_exp_f32_e32 v134, v134
	v_exp_f32_e32 v135, v135
	v_add_f32_e32 v132, 1.0, v132
	v_add_f32_e32 v133, 1.0, v133
	v_add_f32_e32 v134, 1.0, v134
	v_add_f32_e32 v135, 1.0, v135
	v_log_f32_e32 v136, v132
	v_log_f32_e32 v137, v133
	v_log_f32_e32 v138, v134
	v_log_f32_e32 v139, v135
	v_mul_f32_e32 v140, 0x3f317217, v136
	v_mul_f32_e32 v141, 0x3f317217, v137
	v_mul_f32_e32 v142, 0x3f317217, v138
	v_mul_f32_e32 v143, 0x3f317217, v139
	v_fma_f32 v144, v136, s35, -v140
	v_fma_f32 v145, v137, s35, -v141
	v_fma_f32 v146, v138, s35, -v142
	v_fma_f32 v147, v139, s35, -v143
	v_fmac_f32_e32 v144, 0x3377d1cf, v136
	v_fmac_f32_e32 v145, 0x3377d1cf, v137
	v_fmac_f32_e32 v146, 0x3377d1cf, v138
	v_fmac_f32_e32 v147, 0x3377d1cf, v139
	v_fmac_f32_e32 v144, 0x3f317217, v136
	v_fmac_f32_e32 v145, 0x3f317217, v137
	v_fmac_f32_e32 v146, 0x3f317217, v138
	v_fmac_f32_e32 v147, 0x3f317217, v139
	v_min_f32_e32 v128, 0, v128
	v_min_f32_e32 v129, 0, v129
	v_min_f32_e32 v130, 0, v130
	v_min_f32_e32 v131, 0, v131
	v_sub_f32_e32 v128, v128, v144
	v_sub_f32_e32 v129, v129, v145
	v_sub_f32_e32 v130, v130, v146
	v_sub_f32_e32 v131, v131, v147
	v_mul_f32_e32 v106, 0x3d800000, v128
	v_mul_f32_e32 v107, 0x3d800000, v129
	v_mul_f32_e32 v122, 0x3d800000, v130
	v_mul_f32_e32 v123, 0x3d800000, v131
	s_waitcnt lgkmcnt(0)
	s_add_u32 s86, s86, 0x80
	s_addc_u32 s87, s87, 0
	s_load_dwordx16 s[16:31], s[86:87], 0x0
	s_load_dwordx16 s[36:51], s[86:87], 0x40
	v_fma_f32 v128, s0, v10, v74
	v_fma_f32 v129, s0, v11, v75
	v_fma_f32 v130, s64, v42, v76
	v_fma_f32 v131, s64, v43, v77
	v_fmac_f32_e32 v128, s1, v12
	v_fmac_f32_e32 v129, s1, v13
	v_fmac_f32_e32 v130, s65, v44
	v_fmac_f32_e32 v131, s65, v45
	v_fmac_f32_e32 v128, s2, v14
	v_fmac_f32_e32 v129, s2, v15
	v_fmac_f32_e32 v130, s66, v46
	v_fmac_f32_e32 v131, s66, v47
	v_fmac_f32_e32 v128, s3, v16
	v_fmac_f32_e32 v129, s3, v17
	v_fmac_f32_e32 v130, s67, v48
	v_fmac_f32_e32 v131, s67, v49
	v_fmac_f32_e32 v128, s4, v18
	v_fmac_f32_e32 v129, s4, v19
	v_fmac_f32_e32 v130, s68, v50
	v_fmac_f32_e32 v131, s68, v51
	v_fmac_f32_e32 v128, s5, v20
	v_fmac_f32_e32 v129, s5, v21
	v_fmac_f32_e32 v130, s69, v52
	v_fmac_f32_e32 v131, s69, v53
	v_fmac_f32_e32 v128, s6, v22
	v_fmac_f32_e32 v129, s6, v23
	v_fmac_f32_e32 v130, s70, v54
	v_fmac_f32_e32 v131, s70, v55
	v_fmac_f32_e32 v128, s7, v24
	v_fmac_f32_e32 v129, s7, v25
	v_fmac_f32_e32 v130, s71, v56
	v_fmac_f32_e32 v131, s71, v57
	v_fmac_f32_e32 v128, s8, v26
	v_fmac_f32_e32 v129, s8, v27
	v_fmac_f32_e32 v130, s72, v58
	v_fmac_f32_e32 v131, s72, v59
	v_fmac_f32_e32 v128, s9, v28
	v_fmac_f32_e32 v129, s9, v29
	v_fmac_f32_e32 v130, s73, v60
	v_fmac_f32_e32 v131, s73, v61
	v_fmac_f32_e32 v128, s10, v30
	v_fmac_f32_e32 v129, s10, v31
	v_fmac_f32_e32 v130, s74, v62
	v_fmac_f32_e32 v131, s74, v63
	v_fmac_f32_e32 v128, s11, v32
	v_fmac_f32_e32 v129, s11, v33
	v_fmac_f32_e32 v130, s75, v64
	v_fmac_f32_e32 v131, s75, v65
	v_fmac_f32_e32 v128, s12, v34
	v_fmac_f32_e32 v129, s12, v35
	v_fmac_f32_e32 v130, s76, v66
	v_fmac_f32_e32 v131, s76, v67
	v_fmac_f32_e32 v128, s13, v36
	v_fmac_f32_e32 v129, s13, v37
	v_fmac_f32_e32 v130, s77, v68
	v_fmac_f32_e32 v131, s77, v69
	v_fmac_f32_e32 v128, s14, v38
	v_fmac_f32_e32 v129, s14, v39
	v_fmac_f32_e32 v130, s78, v70
	v_fmac_f32_e32 v131, s78, v71
	v_fmac_f32_e32 v128, s15, v40
	v_fmac_f32_e32 v129, s15, v41
	v_fmac_f32_e32 v130, s79, v72
	v_fmac_f32_e32 v131, s79, v73
	v_mul_f32_e64 v132, |v128|, s33
	v_mul_f32_e64 v133, |v129|, s33
	v_mul_f32_e64 v134, |v130|, s33
	v_mul_f32_e64 v135, |v131|, s33
	v_exp_f32_e32 v132, v132
	v_exp_f32_e32 v133, v133
	v_exp_f32_e32 v134, v134
	v_exp_f32_e32 v135, v135
	v_add_f32_e32 v132, 1.0, v132
	v_add_f32_e32 v133, 1.0, v133
	v_add_f32_e32 v134, 1.0, v134
	v_add_f32_e32 v135, 1.0, v135
	v_log_f32_e32 v136, v132
	v_log_f32_e32 v137, v133
	v_log_f32_e32 v138, v134
	v_log_f32_e32 v139, v135
	v_mul_f32_e32 v140, 0x3f317217, v136
	v_mul_f32_e32 v141, 0x3f317217, v137
	v_mul_f32_e32 v142, 0x3f317217, v138
	v_mul_f32_e32 v143, 0x3f317217, v139
	v_fma_f32 v144, v136, s35, -v140
	v_fma_f32 v145, v137, s35, -v141
	v_fma_f32 v146, v138, s35, -v142
	v_fma_f32 v147, v139, s35, -v143
	v_fmac_f32_e32 v144, 0x3377d1cf, v136
	v_fmac_f32_e32 v145, 0x3377d1cf, v137
	v_fmac_f32_e32 v146, 0x3377d1cf, v138
	v_fmac_f32_e32 v147, 0x3377d1cf, v139
	v_fmac_f32_e32 v144, 0x3f317217, v136
	v_fmac_f32_e32 v145, 0x3f317217, v137
	v_fmac_f32_e32 v146, 0x3f317217, v138
	v_fmac_f32_e32 v147, 0x3f317217, v139
	v_min_f32_e32 v128, 0, v128
	v_min_f32_e32 v129, 0, v129
	v_min_f32_e32 v130, 0, v130
	v_min_f32_e32 v131, 0, v131
	v_sub_f32_e32 v128, v128, v144
	v_sub_f32_e32 v129, v129, v145
	v_sub_f32_e32 v130, v130, v146
	v_sub_f32_e32 v131, v131, v147
	v_mul_f32_e32 v108, 0x3d800000, v128
	v_mul_f32_e32 v109, 0x3d800000, v129
	v_mul_f32_e32 v124, 0x3d800000, v130
	v_mul_f32_e32 v125, 0x3d800000, v131
	s_waitcnt lgkmcnt(0)
	v_fma_f32 v128, s16, v10, v74
	v_fma_f32 v129, s16, v11, v75
	v_fma_f32 v130, s36, v42, v76
	v_fma_f32 v131, s36, v43, v77
	v_fmac_f32_e32 v128, s17, v12
	v_fmac_f32_e32 v129, s17, v13
	v_fmac_f32_e32 v130, s37, v44
	v_fmac_f32_e32 v131, s37, v45
	v_fmac_f32_e32 v128, s18, v14
	v_fmac_f32_e32 v129, s18, v15
	v_fmac_f32_e32 v130, s38, v46
	v_fmac_f32_e32 v131, s38, v47
	v_fmac_f32_e32 v128, s19, v16
	v_fmac_f32_e32 v129, s19, v17
	v_fmac_f32_e32 v130, s39, v48
	v_fmac_f32_e32 v131, s39, v49
	v_fmac_f32_e32 v128, s20, v18
	v_fmac_f32_e32 v129, s20, v19
	v_fmac_f32_e32 v130, s40, v50
	v_fmac_f32_e32 v131, s40, v51
	v_fmac_f32_e32 v128, s21, v20
	v_fmac_f32_e32 v129, s21, v21
	v_fmac_f32_e32 v130, s41, v52
	v_fmac_f32_e32 v131, s41, v53
	v_fmac_f32_e32 v128, s22, v22
	v_fmac_f32_e32 v129, s22, v23
	v_fmac_f32_e32 v130, s42, v54
	v_fmac_f32_e32 v131, s42, v55
	v_fmac_f32_e32 v128, s23, v24
	v_fmac_f32_e32 v129, s23, v25
	v_fmac_f32_e32 v130, s43, v56
	v_fmac_f32_e32 v131, s43, v57
	v_fmac_f32_e32 v128, s24, v26
	v_fmac_f32_e32 v129, s24, v27
	v_fmac_f32_e32 v130, s44, v58
	v_fmac_f32_e32 v131, s44, v59
	v_fmac_f32_e32 v128, s25, v28
	v_fmac_f32_e32 v129, s25, v29
	v_fmac_f32_e32 v130, s45, v60
	v_fmac_f32_e32 v131, s45, v61
	v_fmac_f32_e32 v128, s26, v30
	v_fmac_f32_e32 v129, s26, v31
	v_fmac_f32_e32 v130, s46, v62
	v_fmac_f32_e32 v131, s46, v63
	v_fmac_f32_e32 v128, s27, v32
	v_fmac_f32_e32 v129, s27, v33
	v_fmac_f32_e32 v130, s47, v64
	v_fmac_f32_e32 v131, s47, v65
	v_fmac_f32_e32 v128, s28, v34
	v_fmac_f32_e32 v129, s28, v35
	v_fmac_f32_e32 v130, s48, v66
	v_fmac_f32_e32 v131, s48, v67
	v_fmac_f32_e32 v128, s29, v36
	v_fmac_f32_e32 v129, s29, v37
	v_fmac_f32_e32 v130, s49, v68
	v_fmac_f32_e32 v131, s49, v69
	v_fmac_f32_e32 v128, s30, v38
	v_fmac_f32_e32 v129, s30, v39
	v_fmac_f32_e32 v130, s50, v70
	v_fmac_f32_e32 v131, s50, v71
	v_fmac_f32_e32 v128, s31, v40
	v_fmac_f32_e32 v129, s31, v41
	v_fmac_f32_e32 v130, s51, v72
	v_fmac_f32_e32 v131, s51, v73
	v_mul_f32_e64 v132, |v128|, s33
	v_mul_f32_e64 v133, |v129|, s33
	v_mul_f32_e64 v134, |v130|, s33
	v_mul_f32_e64 v135, |v131|, s33
	v_exp_f32_e32 v132, v132
	v_exp_f32_e32 v133, v133
	v_exp_f32_e32 v134, v134
	v_exp_f32_e32 v135, v135
	v_add_f32_e32 v132, 1.0, v132
	v_add_f32_e32 v133, 1.0, v133
	v_add_f32_e32 v134, 1.0, v134
	v_add_f32_e32 v135, 1.0, v135
	v_log_f32_e32 v136, v132
	v_log_f32_e32 v137, v133
	v_log_f32_e32 v138, v134
	v_log_f32_e32 v139, v135
	v_mul_f32_e32 v140, 0x3f317217, v136
	v_mul_f32_e32 v141, 0x3f317217, v137
	v_mul_f32_e32 v142, 0x3f317217, v138
	v_mul_f32_e32 v143, 0x3f317217, v139
	v_fma_f32 v144, v136, s35, -v140
	v_fma_f32 v145, v137, s35, -v141
	v_fma_f32 v146, v138, s35, -v142
	v_fma_f32 v147, v139, s35, -v143
	v_fmac_f32_e32 v144, 0x3377d1cf, v136
	v_fmac_f32_e32 v145, 0x3377d1cf, v137
	v_fmac_f32_e32 v146, 0x3377d1cf, v138
	v_fmac_f32_e32 v147, 0x3377d1cf, v139
	v_fmac_f32_e32 v144, 0x3f317217, v136
	v_fmac_f32_e32 v145, 0x3f317217, v137
	v_fmac_f32_e32 v146, 0x3f317217, v138
	v_fmac_f32_e32 v147, 0x3f317217, v139
	v_min_f32_e32 v128, 0, v128
	v_min_f32_e32 v129, 0, v129
	v_min_f32_e32 v130, 0, v130
	v_min_f32_e32 v131, 0, v131
	v_sub_f32_e32 v128, v128, v144
	v_sub_f32_e32 v129, v129, v145
	v_sub_f32_e32 v130, v130, v146
	v_sub_f32_e32 v131, v131, v147
	v_mul_f32_e32 v110, 0x3d800000, v128
	v_mul_f32_e32 v111, 0x3d800000, v129
	v_mul_f32_e32 v126, 0x3d800000, v130
	v_mul_f32_e32 v127, 0x3d800000, v131
	v_add_f32_e32 v98, v98, v96
	v_add_f32_e32 v99, v99, v97
	v_add_f32_e32 v100, v100, v98
	v_add_f32_e32 v101, v101, v99
	v_add_f32_e32 v102, v102, v100
	v_add_f32_e32 v103, v103, v101
	v_add_f32_e32 v104, v104, v102
	v_add_f32_e32 v105, v105, v103
	v_add_f32_e32 v106, v106, v104
	v_add_f32_e32 v107, v107, v105
	v_add_f32_e32 v108, v108, v106
	v_add_f32_e32 v109, v109, v107
	v_add_f32_e32 v110, v110, v108
	v_add_f32_e32 v111, v111, v109
	v_add_f32_e32 v124, v124, v126
	v_add_f32_e32 v125, v125, v127
	v_add_f32_e32 v122, v122, v124
	v_add_f32_e32 v123, v123, v125
	v_add_f32_e32 v120, v120, v122
	v_add_f32_e32 v121, v121, v123
	v_add_f32_e32 v118, v118, v120
	v_add_f32_e32 v119, v119, v121
	v_add_f32_e32 v116, v116, v118
	v_add_f32_e32 v117, v117, v119
	v_add_f32_e32 v114, v114, v116
	v_add_f32_e32 v115, v115, v117
	v_add_f32_e32 v112, v112, v114
	v_add_f32_e32 v113, v113, v115
	s_lshl_b32 s92, s98, 13
	s_lshl_b32 s93, s32, 9
	s_add_i32 s93, s93, s92
	v_add_u32_e32 v184, s93, v3
	v_add_u32_e32 v185, s92, v3
	ds_write_b64 v184, v[110:111]
	ds_write_b64 v184, v[112:113] offset:4096
	s_waitcnt lgkmcnt(0)
	s_barrier
	ds_read_b64 v[152:153], v185 offset:0
	ds_read_b64 v[154:155], v185 offset:512
	ds_read_b64 v[156:157], v185 offset:1024
	ds_read_b64 v[158:159], v185 offset:1536
	ds_read_b64 v[160:161], v185 offset:2048
	ds_read_b64 v[162:163], v185 offset:2560
	ds_read_b64 v[164:165], v185 offset:3072
	ds_read_b64 v[166:167], v185 offset:3584
	ds_read_b64 v[168:169], v185 offset:4096
	ds_read_b64 v[170:171], v185 offset:4608
	ds_read_b64 v[172:173], v185 offset:5120
	ds_read_b64 v[174:175], v185 offset:5632
	ds_read_b64 v[176:177], v185 offset:6144
	ds_read_b64 v[178:179], v185 offset:6656
	ds_read_b64 v[180:181], v185 offset:7168
	ds_read_b64 v[182:183], v185 offset:7680
	v_mov_b32_e32 v132, 0
	v_mov_b32_e32 v133, 0
	v_mov_b32_e32 v134, 0
	v_mov_b32_e32 v135, 0
	s_waitcnt lgkmcnt(0)
	s_cmp_le_u32 s32, 0
	s_cbranch_scc1 .Lp7_offf_done
	v_add_f32_e32 v132, v132, v152
	v_add_f32_e32 v133, v133, v153
	s_cmp_le_u32 s32, 1
	s_cbranch_scc1 .Lp7_offf_done
	v_add_f32_e32 v132, v132, v154
	v_add_f32_e32 v133, v133, v155
	s_cmp_le_u32 s32, 2
	s_cbranch_scc1 .Lp7_offf_done
	v_add_f32_e32 v132, v132, v156
	v_add_f32_e32 v133, v133, v157
	s_cmp_le_u32 s32, 3
	s_cbranch_scc1 .Lp7_offf_done
	v_add_f32_e32 v132, v132, v158
	v_add_f32_e32 v133, v133, v159
	s_cmp_le_u32 s32, 4
	s_cbranch_scc1 .Lp7_offf_done
	v_add_f32_e32 v132, v132, v160
	v_add_f32_e32 v133, v133, v161
	s_cmp_le_u32 s32, 5
	s_cbranch_scc1 .Lp7_offf_done
	v_add_f32_e32 v132, v132, v162
	v_add_f32_e32 v133, v133, v163
	s_cmp_le_u32 s32, 6
	s_cbranch_scc1 .Lp7_offf_done
	v_add_f32_e32 v132, v132, v164
	v_add_f32_e32 v133, v133, v165
.Lp7_offf_done:
	s_cmp_ge_u32 s32, 7
	s_cbranch_scc1 .Lp7_offb_done
	v_add_f32_e32 v134, v134, v182
	v_add_f32_e32 v135, v135, v183
	s_cmp_ge_u32 s32, 6
	s_cbranch_scc1 .Lp7_offb_done
	v_add_f32_e32 v134, v134, v180
	v_add_f32_e32 v135, v135, v181
	s_cmp_ge_u32 s32, 5
	s_cbranch_scc1 .Lp7_offb_done
	v_add_f32_e32 v134, v134, v178
	v_add_f32_e32 v135, v135, v179
	s_cmp_ge_u32 s32, 4
	s_cbranch_scc1 .Lp7_offb_done
	v_add_f32_e32 v134, v134, v176
	v_add_f32_e32 v135, v135, v177
	s_cmp_ge_u32 s32, 3
	s_cbranch_scc1 .Lp7_offb_done
	v_add_f32_e32 v134, v134, v174
	v_add_f32_e32 v135, v135, v175
	s_cmp_ge_u32 s32, 2
	s_cbranch_scc1 .Lp7_offb_done
	v_add_f32_e32 v134, v134, v172
	v_add_f32_e32 v135, v135, v173
	s_cmp_ge_u32 s32, 1
	s_cbranch_scc1 .Lp7_offb_done
	v_add_f32_e32 v134, v134, v170
	v_add_f32_e32 v135, v135, v171
.Lp7_offb_done:
	s_cmp_lg_u32 s32, 0
	s_cbranch_scc1 .Lp7_dec_done
	v_add_f32_e32 v136, v152, v154
	v_add_f32_e32 v137, v153, v155
	v_add_f32_e32 v138, v168, v170
	v_add_f32_e32 v139, v169, v171
	v_add_f32_e32 v136, v136, v156
	v_add_f32_e32 v137, v137, v157
	v_add_f32_e32 v138, v138, v172
	v_add_f32_e32 v139, v139, v173
	v_add_f32_e32 v136, v136, v158
	v_add_f32_e32 v137, v137, v159
	v_add_f32_e32 v138, v138, v174
	v_add_f32_e32 v139, v139, v175
	v_add_f32_e32 v136, v136, v160
	v_add_f32_e32 v137, v137, v161
	v_add_f32_e32 v138, v138, v176
	v_add_f32_e32 v139, v139, v177
	v_add_f32_e32 v136, v136, v162
	v_add_f32_e32 v137, v137, v163
	v_add_f32_e32 v138, v138, v178
	v_add_f32_e32 v139, v139, v179
	v_add_f32_e32 v136, v136, v164
	v_add_f32_e32 v137, v137, v165
	v_add_f32_e32 v138, v138, v180
	v_add_f32_e32 v139, v139, v181
	v_add_f32_e32 v136, v136, v166
	v_add_f32_e32 v137, v137, v167
	v_add_f32_e32 v138, v138, v182
	v_add_f32_e32 v139, v139, v183
	v_mul_f32_e32 v136, 0x3fb8aa3b, v136
	v_mul_f32_e32 v137, 0x3fb8aa3b, v137
	v_mul_f32_e32 v138, 0x3fb8aa3b, v138
	v_mul_f32_e32 v139, 0x3fb8aa3b, v139
	v_exp_f32_e32 v136, v136
	v_exp_f32_e32 v137, v137
	v_exp_f32_e32 v138, v138
	v_exp_f32_e32 v139, v139
	s_lshl_b32 s92, s99, 2
	s_add_i32 s92, s92, s101
	s_mul_i32 s92, s92, 36
	s_add_i32 s92, s92, s100
	s_lshl_b32 s92, s92, 9
	s_add_u32 s52, s88, 0x115d000
	s_addc_u32 s53, s89, 0
	s_add_u32 s52, s52, s92
	s_addc_u32 s53, s53, 0
	global_store_dwordx2 v3, v[136:137], s[52:53]
	s_add_u32 s52, s52, 0x90000
	s_addc_u32 s53, s53, 0
	global_store_dwordx2 v3, v[138:139], s[52:53]
.Lp7_dec_done:
	s_mov_b64 s[52:53], s[80:81]
	s_mov_b64 s[54:55], s[82:83]
	v_add_f32_e32 v136, v96, v132
	v_add_f32_e32 v137, v97, v133
	v_add_f32_e32 v138, v112, v134
	v_add_f32_e32 v139, v113, v135
	v_mul_f32_e32 v136, 0xbfb8aa3b, v136
	v_mul_f32_e32 v137, 0xbfb8aa3b, v137
	v_mul_f32_e32 v138, 0xbfb8aa3b, v138
	v_mul_f32_e32 v139, 0xbfb8aa3b, v139
	v_exp_f32_e32 v136, v136
	v_exp_f32_e32 v137, v137
	v_exp_f32_e32 v138, v138
	v_exp_f32_e32 v139, v139
	v_lshlrev_b32_e32 v140, 16, v80
	v_and_b32_e32 v141, 0xffff0000, v80
	v_mul_f32_e32 v136, v136, v140
	v_mul_f32_e32 v137, v137, v141
	v_mul_f32_e32 v138, v138, v140
	v_mul_f32_e32 v139, v139, v141
	v_cvt_pk_bf16_f32 v142, v136, v137
	v_cvt_pk_bf16_f32 v143, v138, v139
	global_store_dword v2, v142, s[52:53] offset:1024
	global_store_dword v2, v143, s[54:55]
	s_add_u32 s52, s52, 0x1800
	s_addc_u32 s53, s53, 0
	s_add_u32 s54, s54, 0x400
	s_addc_u32 s55, s55, 0
	v_add_f32_e32 v136, v98, v132
	v_add_f32_e32 v137, v99, v133
	v_add_f32_e32 v138, v114, v134
	v_add_f32_e32 v139, v115, v135
	v_mul_f32_e32 v136, 0xbfb8aa3b, v136
	v_mul_f32_e32 v137, 0xbfb8aa3b, v137
	v_mul_f32_e32 v138, 0xbfb8aa3b, v138
	v_mul_f32_e32 v139, 0xbfb8aa3b, v139
	v_exp_f32_e32 v136, v136
	v_exp_f32_e32 v137, v137
	v_exp_f32_e32 v138, v138
	v_exp_f32_e32 v139, v139
	v_lshlrev_b32_e32 v140, 16, v81
	v_and_b32_e32 v141, 0xffff0000, v81
	v_mul_f32_e32 v136, v136, v140
	v_mul_f32_e32 v137, v137, v141
	v_mul_f32_e32 v138, v138, v140
	v_mul_f32_e32 v139, v139, v141
	v_cvt_pk_bf16_f32 v142, v136, v137
	v_cvt_pk_bf16_f32 v143, v138, v139
	global_store_dword v2, v142, s[52:53] offset:1024
	global_store_dword v2, v143, s[54:55]
	s_add_u32 s52, s52, 0x1800
	s_addc_u32 s53, s53, 0
	s_add_u32 s54, s54, 0x400
	s_addc_u32 s55, s55, 0
	v_add_f32_e32 v136, v100, v132
	v_add_f32_e32 v137, v101, v133
	v_add_f32_e32 v138, v116, v134
	v_add_f32_e32 v139, v117, v135
	v_mul_f32_e32 v136, 0xbfb8aa3b, v136
	v_mul_f32_e32 v137, 0xbfb8aa3b, v137
	v_mul_f32_e32 v138, 0xbfb8aa3b, v138
	v_mul_f32_e32 v139, 0xbfb8aa3b, v139
	v_exp_f32_e32 v136, v136
	v_exp_f32_e32 v137, v137
	v_exp_f32_e32 v138, v138
	v_exp_f32_e32 v139, v139
	v_lshlrev_b32_e32 v140, 16, v82
	v_and_b32_e32 v141, 0xffff0000, v82
	v_mul_f32_e32 v136, v136, v140
	v_mul_f32_e32 v137, v137, v141
	v_mul_f32_e32 v138, v138, v140
	v_mul_f32_e32 v139, v139, v141
	v_cvt_pk_bf16_f32 v142, v136, v137
	v_cvt_pk_bf16_f32 v143, v138, v139
	global_store_dword v2, v142, s[52:53] offset:1024
	global_store_dword v2, v143, s[54:55]
	s_add_u32 s52, s52, 0x1800
	s_addc_u32 s53, s53, 0
	s_add_u32 s54, s54, 0x400
	s_addc_u32 s55, s55, 0
	v_add_f32_e32 v136, v102, v132
	v_add_f32_e32 v137, v103, v133
	v_add_f32_e32 v138, v118, v134
	v_add_f32_e32 v139, v119, v135
	v_mul_f32_e32 v136, 0xbfb8aa3b, v136
	v_mul_f32_e32 v137, 0xbfb8aa3b, v137
	v_mul_f32_e32 v138, 0xbfb8aa3b, v138
	v_mul_f32_e32 v139, 0xbfb8aa3b, v139
	v_exp_f32_e32 v136, v136
	v_exp_f32_e32 v137, v137
	v_exp_f32_e32 v138, v138
	v_exp_f32_e32 v139, v139
	v_lshlrev_b32_e32 v140, 16, v83
	v_and_b32_e32 v141, 0xffff0000, v83
	v_mul_f32_e32 v136, v136, v140
	v_mul_f32_e32 v137, v137, v141
	v_mul_f32_e32 v138, v138, v140
	v_mul_f32_e32 v139, v139, v141
	v_cvt_pk_bf16_f32 v142, v136, v137
	v_cvt_pk_bf16_f32 v143, v138, v139
	global_store_dword v2, v142, s[52:53] offset:1024
	global_store_dword v2, v143, s[54:55]
	s_add_u32 s52, s52, 0x1800
	s_addc_u32 s53, s53, 0
	s_add_u32 s54, s54, 0x400
	s_addc_u32 s55, s55, 0
	v_add_f32_e32 v136, v104, v132
	v_add_f32_e32 v137, v105, v133
	v_add_f32_e32 v138, v120, v134
	v_add_f32_e32 v139, v121, v135
	v_mul_f32_e32 v136, 0xbfb8aa3b, v136
	v_mul_f32_e32 v137, 0xbfb8aa3b, v137
	v_mul_f32_e32 v138, 0xbfb8aa3b, v138
	v_mul_f32_e32 v139, 0xbfb8aa3b, v139
	v_exp_f32_e32 v136, v136
	v_exp_f32_e32 v137, v137
	v_exp_f32_e32 v138, v138
	v_exp_f32_e32 v139, v139
	v_lshlrev_b32_e32 v140, 16, v84
	v_and_b32_e32 v141, 0xffff0000, v84
	v_mul_f32_e32 v136, v136, v140
	v_mul_f32_e32 v137, v137, v141
	v_mul_f32_e32 v138, v138, v140
	v_mul_f32_e32 v139, v139, v141
	v_cvt_pk_bf16_f32 v142, v136, v137
	v_cvt_pk_bf16_f32 v143, v138, v139
	global_store_dword v2, v142, s[52:53] offset:1024
	global_store_dword v2, v143, s[54:55]
	s_add_u32 s52, s52, 0x1800
	s_addc_u32 s53, s53, 0
	s_add_u32 s54, s54, 0x400
	s_addc_u32 s55, s55, 0
	v_add_f32_e32 v136, v106, v132
	v_add_f32_e32 v137, v107, v133
	v_add_f32_e32 v138, v122, v134
	v_add_f32_e32 v139, v123, v135
	v_mul_f32_e32 v136, 0xbfb8aa3b, v136
	v_mul_f32_e32 v137, 0xbfb8aa3b, v137
	v_mul_f32_e32 v138, 0xbfb8aa3b, v138
	v_mul_f32_e32 v139, 0xbfb8aa3b, v139
	v_exp_f32_e32 v136, v136
	v_exp_f32_e32 v137, v137
	v_exp_f32_e32 v138, v138
	v_exp_f32_e32 v139, v139
	v_lshlrev_b32_e32 v140, 16, v85
	v_and_b32_e32 v141, 0xffff0000, v85
	v_mul_f32_e32 v136, v136, v140
	v_mul_f32_e32 v137, v137, v141
	v_mul_f32_e32 v138, v138, v140
	v_mul_f32_e32 v139, v139, v141
	v_cvt_pk_bf16_f32 v142, v136, v137
	v_cvt_pk_bf16_f32 v143, v138, v139
	global_store_dword v2, v142, s[52:53] offset:1024
	global_store_dword v2, v143, s[54:55]
	s_add_u32 s52, s52, 0x1800
	s_addc_u32 s53, s53, 0
	s_add_u32 s54, s54, 0x400
	s_addc_u32 s55, s55, 0
	v_add_f32_e32 v136, v108, v132
	v_add_f32_e32 v137, v109, v133
	v_add_f32_e32 v138, v124, v134
	v_add_f32_e32 v139, v125, v135
	v_mul_f32_e32 v136, 0xbfb8aa3b, v136
	v_mul_f32_e32 v137, 0xbfb8aa3b, v137
	v_mul_f32_e32 v138, 0xbfb8aa3b, v138
	v_mul_f32_e32 v139, 0xbfb8aa3b, v139
	v_exp_f32_e32 v136, v136
	v_exp_f32_e32 v137, v137
	v_exp_f32_e32 v138, v138
	v_exp_f32_e32 v139, v139
	v_lshlrev_b32_e32 v140, 16, v86
	v_and_b32_e32 v141, 0xffff0000, v86
	v_mul_f32_e32 v136, v136, v140
	v_mul_f32_e32 v137, v137, v141
	v_mul_f32_e32 v138, v138, v140
	v_mul_f32_e32 v139, v139, v141
	v_cvt_pk_bf16_f32 v142, v136, v137
	v_cvt_pk_bf16_f32 v143, v138, v139
	global_store_dword v2, v142, s[52:53] offset:1024
	global_store_dword v2, v143, s[54:55]
	s_add_u32 s52, s52, 0x1800
	s_addc_u32 s53, s53, 0
	s_add_u32 s54, s54, 0x400
	s_addc_u32 s55, s55, 0
	v_add_f32_e32 v136, v110, v132
	v_add_f32_e32 v137, v111, v133
	v_add_f32_e32 v138, v126, v134
	v_add_f32_e32 v139, v127, v135
	v_mul_f32_e32 v136, 0xbfb8aa3b, v136
	v_mul_f32_e32 v137, 0xbfb8aa3b, v137
	v_mul_f32_e32 v138, 0xbfb8aa3b, v138
	v_mul_f32_e32 v139, 0xbfb8aa3b, v139
	v_exp_f32_e32 v136, v136
	v_exp_f32_e32 v137, v137
	v_exp_f32_e32 v138, v138
	v_exp_f32_e32 v139, v139
	v_lshlrev_b32_e32 v140, 16, v87
	v_and_b32_e32 v141, 0xffff0000, v87
	v_mul_f32_e32 v136, v136, v140
	v_mul_f32_e32 v137, v137, v141
	v_mul_f32_e32 v138, v138, v140
	v_mul_f32_e32 v139, v139, v141
	v_cvt_pk_bf16_f32 v142, v136, v137
	v_cvt_pk_bf16_f32 v143, v138, v139
	global_store_dword v2, v142, s[52:53] offset:1024
	global_store_dword v2, v143, s[54:55]
	s_cmp_lt_u32 s100, 4
	s_cbranch_scc1 .Lp7_noq_store
	s_mov_b64 s[52:53], s[80:81]
	s_mov_b64 s[54:55], s[84:85]
	v_add_f32_e32 v136, v96, v132
	v_add_f32_e32 v137, v97, v133
	v_add_f32_e32 v138, v112, v134
	v_add_f32_e32 v139, v113, v135
	v_mul_f32_e32 v136, 0x3fb8aa3b, v136
	v_mul_f32_e32 v137, 0x3fb8aa3b, v137
	v_mul_f32_e32 v138, 0x3fb8aa3b, v138
	v_mul_f32_e32 v139, 0x3fb8aa3b, v139
	v_exp_f32_e32 v136, v136
	v_exp_f32_e32 v137, v137
	v_exp_f32_e32 v138, v138
	v_exp_f32_e32 v139, v139
	v_lshlrev_b32_e32 v140, 16, v88
	v_and_b32_e32 v141, 0xffff0000, v88
	v_mul_f32_e32 v136, v140, v136
	v_mul_f32_e32 v137, v141, v137
	v_mul_f32_e32 v138, v140, v138
	v_mul_f32_e32 v139, v141, v139
	v_cvt_pk_bf16_f32 v142, v136, v137
	v_cvt_pk_bf16_f32 v143, v138, v139
	global_store_dword v2, v142, s[52:53]
	global_store_dword v2, v143, s[54:55]
	s_add_u32 s52, s52, 0x1800
	s_addc_u32 s53, s53, 0
	s_add_u32 s54, s54, 0x400
	s_addc_u32 s55, s55, 0
	v_add_f32_e32 v136, v98, v132
	v_add_f32_e32 v137, v99, v133
	v_add_f32_e32 v138, v114, v134
	v_add_f32_e32 v139, v115, v135
	v_mul_f32_e32 v136, 0x3fb8aa3b, v136
	v_mul_f32_e32 v137, 0x3fb8aa3b, v137
	v_mul_f32_e32 v138, 0x3fb8aa3b, v138
	v_mul_f32_e32 v139, 0x3fb8aa3b, v139
	v_exp_f32_e32 v136, v136
	v_exp_f32_e32 v137, v137
	v_exp_f32_e32 v138, v138
	v_exp_f32_e32 v139, v139
	v_lshlrev_b32_e32 v140, 16, v89
	v_and_b32_e32 v141, 0xffff0000, v89
	v_mul_f32_e32 v136, v140, v136
	v_mul_f32_e32 v137, v141, v137
	v_mul_f32_e32 v138, v140, v138
	v_mul_f32_e32 v139, v141, v139
	v_cvt_pk_bf16_f32 v142, v136, v137
	v_cvt_pk_bf16_f32 v143, v138, v139
	global_store_dword v2, v142, s[52:53]
	global_store_dword v2, v143, s[54:55]
	s_add_u32 s52, s52, 0x1800
	s_addc_u32 s53, s53, 0
	s_add_u32 s54, s54, 0x400
	s_addc_u32 s55, s55, 0
	v_add_f32_e32 v136, v100, v132
	v_add_f32_e32 v137, v101, v133
	v_add_f32_e32 v138, v116, v134
	v_add_f32_e32 v139, v117, v135
	v_mul_f32_e32 v136, 0x3fb8aa3b, v136
	v_mul_f32_e32 v137, 0x3fb8aa3b, v137
	v_mul_f32_e32 v138, 0x3fb8aa3b, v138
	v_mul_f32_e32 v139, 0x3fb8aa3b, v139
	v_exp_f32_e32 v136, v136
	v_exp_f32_e32 v137, v137
	v_exp_f32_e32 v138, v138
	v_exp_f32_e32 v139, v139
	v_lshlrev_b32_e32 v140, 16, v90
	v_and_b32_e32 v141, 0xffff0000, v90
	v_mul_f32_e32 v136, v140, v136
	v_mul_f32_e32 v137, v141, v137
	v_mul_f32_e32 v138, v140, v138
	v_mul_f32_e32 v139, v141, v139
	v_cvt_pk_bf16_f32 v142, v136, v137
	v_cvt_pk_bf16_f32 v143, v138, v139
	global_store_dword v2, v142, s[52:53]
	global_store_dword v2, v143, s[54:55]
	s_add_u32 s52, s52, 0x1800
	s_addc_u32 s53, s53, 0
	s_add_u32 s54, s54, 0x400
	s_addc_u32 s55, s55, 0
	v_add_f32_e32 v136, v102, v132
	v_add_f32_e32 v137, v103, v133
	v_add_f32_e32 v138, v118, v134
	v_add_f32_e32 v139, v119, v135
	v_mul_f32_e32 v136, 0x3fb8aa3b, v136
	v_mul_f32_e32 v137, 0x3fb8aa3b, v137
	v_mul_f32_e32 v138, 0x3fb8aa3b, v138
	v_mul_f32_e32 v139, 0x3fb8aa3b, v139
	v_exp_f32_e32 v136, v136
	v_exp_f32_e32 v137, v137
	v_exp_f32_e32 v138, v138
	v_exp_f32_e32 v139, v139
	v_lshlrev_b32_e32 v140, 16, v91
	v_and_b32_e32 v141, 0xffff0000, v91
	v_mul_f32_e32 v136, v140, v136
	v_mul_f32_e32 v137, v141, v137
	v_mul_f32_e32 v138, v140, v138
	v_mul_f32_e32 v139, v141, v139
	v_cvt_pk_bf16_f32 v142, v136, v137
	v_cvt_pk_bf16_f32 v143, v138, v139
	global_store_dword v2, v142, s[52:53]
	global_store_dword v2, v143, s[54:55]
	s_add_u32 s52, s52, 0x1800
	s_addc_u32 s53, s53, 0
	s_add_u32 s54, s54, 0x400
	s_addc_u32 s55, s55, 0
	v_add_f32_e32 v136, v104, v132
	v_add_f32_e32 v137, v105, v133
	v_add_f32_e32 v138, v120, v134
	v_add_f32_e32 v139, v121, v135
	v_mul_f32_e32 v136, 0x3fb8aa3b, v136
	v_mul_f32_e32 v137, 0x3fb8aa3b, v137
	v_mul_f32_e32 v138, 0x3fb8aa3b, v138
	v_mul_f32_e32 v139, 0x3fb8aa3b, v139
	v_exp_f32_e32 v136, v136
	v_exp_f32_e32 v137, v137
	v_exp_f32_e32 v138, v138
	v_exp_f32_e32 v139, v139
	v_lshlrev_b32_e32 v140, 16, v92
	v_and_b32_e32 v141, 0xffff0000, v92
	v_mul_f32_e32 v136, v140, v136
	v_mul_f32_e32 v137, v141, v137
	v_mul_f32_e32 v138, v140, v138
	v_mul_f32_e32 v139, v141, v139
	v_cvt_pk_bf16_f32 v142, v136, v137
	v_cvt_pk_bf16_f32 v143, v138, v139
	global_store_dword v2, v142, s[52:53]
	global_store_dword v2, v143, s[54:55]
	s_add_u32 s52, s52, 0x1800
	s_addc_u32 s53, s53, 0
	s_add_u32 s54, s54, 0x400
	s_addc_u32 s55, s55, 0
	v_add_f32_e32 v136, v106, v132
	v_add_f32_e32 v137, v107, v133
	v_add_f32_e32 v138, v122, v134
	v_add_f32_e32 v139, v123, v135
	v_mul_f32_e32 v136, 0x3fb8aa3b, v136
	v_mul_f32_e32 v137, 0x3fb8aa3b, v137
	v_mul_f32_e32 v138, 0x3fb8aa3b, v138
	v_mul_f32_e32 v139, 0x3fb8aa3b, v139
	v_exp_f32_e32 v136, v136
	v_exp_f32_e32 v137, v137
	v_exp_f32_e32 v138, v138
	v_exp_f32_e32 v139, v139
	v_lshlrev_b32_e32 v140, 16, v93
	v_and_b32_e32 v141, 0xffff0000, v93
	v_mul_f32_e32 v136, v140, v136
	v_mul_f32_e32 v137, v141, v137
	v_mul_f32_e32 v138, v140, v138
	v_mul_f32_e32 v139, v141, v139
	v_cvt_pk_bf16_f32 v142, v136, v137
	v_cvt_pk_bf16_f32 v143, v138, v139
	global_store_dword v2, v142, s[52:53]
	global_store_dword v2, v143, s[54:55]
	s_add_u32 s52, s52, 0x1800
	s_addc_u32 s53, s53, 0
	s_add_u32 s54, s54, 0x400
	s_addc_u32 s55, s55, 0
	v_add_f32_e32 v136, v108, v132
	v_add_f32_e32 v137, v109, v133
	v_add_f32_e32 v138, v124, v134
	v_add_f32_e32 v139, v125, v135
	v_mul_f32_e32 v136, 0x3fb8aa3b, v136
	v_mul_f32_e32 v137, 0x3fb8aa3b, v137
	v_mul_f32_e32 v138, 0x3fb8aa3b, v138
	v_mul_f32_e32 v139, 0x3fb8aa3b, v139
	v_exp_f32_e32 v136, v136
	v_exp_f32_e32 v137, v137
	v_exp_f32_e32 v138, v138
	v_exp_f32_e32 v139, v139
	v_lshlrev_b32_e32 v140, 16, v94
	v_and_b32_e32 v141, 0xffff0000, v94
	v_mul_f32_e32 v136, v140, v136
	v_mul_f32_e32 v137, v141, v137
	v_mul_f32_e32 v138, v140, v138
	v_mul_f32_e32 v139, v141, v139
	v_cvt_pk_bf16_f32 v142, v136, v137
	v_cvt_pk_bf16_f32 v143, v138, v139
	global_store_dword v2, v142, s[52:53]
	global_store_dword v2, v143, s[54:55]
	s_add_u32 s52, s52, 0x1800
	s_addc_u32 s53, s53, 0
	s_add_u32 s54, s54, 0x400
	s_addc_u32 s55, s55, 0
	v_add_f32_e32 v136, v110, v132
	v_add_f32_e32 v137, v111, v133
	v_add_f32_e32 v138, v126, v134
	v_add_f32_e32 v139, v127, v135
	v_mul_f32_e32 v136, 0x3fb8aa3b, v136
	v_mul_f32_e32 v137, 0x3fb8aa3b, v137
	v_mul_f32_e32 v138, 0x3fb8aa3b, v138
	v_mul_f32_e32 v139, 0x3fb8aa3b, v139
	v_exp_f32_e32 v136, v136
	v_exp_f32_e32 v137, v137
	v_exp_f32_e32 v138, v138
	v_exp_f32_e32 v139, v139
	v_lshlrev_b32_e32 v140, 16, v95
	v_and_b32_e32 v141, 0xffff0000, v95
	v_mul_f32_e32 v136, v140, v136
	v_mul_f32_e32 v137, v141, v137
	v_mul_f32_e32 v138, v140, v138
	v_mul_f32_e32 v139, v141, v139
	v_cvt_pk_bf16_f32 v142, v136, v137
	v_cvt_pk_bf16_f32 v143, v138, v139
	global_store_dword v2, v142, s[52:53]
	global_store_dword v2, v143, s[54:55]
.Lp7_noq_store:
	v_readlane_b32 s69, v251, 49
	s_xor_b32 s98, s98, 1
	s_nop 3
	s_add_i32 s34, s34, s69
	s_cmpk_lt_i32 s34, 0x480
	s_cbranch_scc1 .Lp7_item
	v_readlane_b32 s18, v252, 0
	v_readlane_b32 s19, v252, 1
	v_readlane_b32 s24, v252, 2
	v_readlane_b32 s25, v252, 3
	v_readlane_b32 s26, v252, 4
	v_readlane_b32 s27, v252, 5
	s_add_u32 s36, s88, 0x115d000
	s_addc_u32 s37, s89, 0
	s_nop 3
